# P0 adaLN: skip the silu(c) LDS staging for a block's second item when its k-split is unchanged
# speedup vs baseline: 1.0047x; 1.0047x over previous
.LBB0_14:
	s_or_b64 exec, exec, s[4:5]
	s_load_dwordx16 s[68:83], s[0:1], 0x0
	s_load_dwordx16 s[12:27], s[0:1], 0x40
	s_add_u32 s10, s50, 0x40c0000
	s_addc_u32 s11, s51, 0
	s_cmpk_gt_i32 s96, 0x17f
	v_lshlrev_b32_e32 v1, 2, v10
	s_waitcnt lgkmcnt(0)
	v_writelane_b32 v254, s12, 2
	s_nop 1
	v_writelane_b32 v254, s13, 3
	v_writelane_b32 v254, s14, 4
	v_writelane_b32 v254, s15, 5
	v_writelane_b32 v254, s16, 6
	v_writelane_b32 v254, s17, 7
	v_writelane_b32 v254, s18, 8
	v_writelane_b32 v254, s19, 9
	v_writelane_b32 v254, s20, 10
	v_writelane_b32 v254, s21, 11
	v_writelane_b32 v254, s22, 12
	v_writelane_b32 v254, s23, 13
	v_writelane_b32 v254, s24, 14
	v_writelane_b32 v254, s25, 15
	v_writelane_b32 v254, s26, 16
	v_writelane_b32 v254, s27, 17
	s_load_dwordx16 s[12:27], s[0:1], 0x80
	s_waitcnt lgkmcnt(0)
	v_writelane_b32 v254, s12, 18
	s_nop 1
	v_writelane_b32 v254, s13, 19
	v_writelane_b32 v254, s14, 20
	v_writelane_b32 v254, s15, 21
	v_writelane_b32 v254, s16, 22
	v_writelane_b32 v254, s17, 23
	v_writelane_b32 v254, s18, 24
	v_writelane_b32 v254, s19, 25
	v_writelane_b32 v254, s20, 26
	v_writelane_b32 v254, s21, 27
	v_writelane_b32 v254, s22, 28
	v_writelane_b32 v254, s23, 29
	v_writelane_b32 v254, s24, 30
	v_writelane_b32 v254, s25, 31
	v_writelane_b32 v254, s26, 32
	v_writelane_b32 v254, s27, 33
	s_cbranch_scc1 .LBB0_28
	s_movk_i32 s0, 0x1200
	v_cmp_gt_i32_e64 s[4:5], s0, v10
	v_ashrrev_i32_e32 v3, 1, v10
	v_and_b32_e32 v4, 28, v1
	s_movk_i32 s0, 0xffe0
	v_and_or_b32 v154, v3, s0, v4
	v_mbcnt_lo_u32_b32 v3, -1, 0
	v_mbcnt_hi_u32_b32 v3, -1, v3
	v_and_b32_e32 v5, 64, v3
	v_xor_b32_e32 v4, 8, v3
	v_add_u32_e32 v5, 64, v5
	v_cmp_lt_i32_e32 vcc, v4, v5
	v_readlane_b32 s12, v254, 2
	v_readlane_b32 s16, v254, 6
	v_cndmask_b32_e32 v4, v3, v4, vcc
	v_lshlrev_b32_e32 v156, 2, v4
	v_xor_b32_e32 v4, 16, v3
	v_cmp_lt_i32_e32 vcc, v4, v5
	v_and_b32_e32 v2, 63, v10
	v_bfe_u32 v12, v10, 3, 3
	v_cndmask_b32_e32 v4, v3, v4, vcc
	v_lshlrev_b32_e32 v157, 2, v4
	v_xor_b32_e32 v4, 32, v3
	v_cmp_lt_i32_e32 vcc, v4, v5
	v_mov_b32_e32 v15, 0
	v_readlane_b32 s17, v254, 7
	v_cndmask_b32_e32 v3, v3, v4, vcc
	v_readlane_b32 s20, v254, 10
	v_readlane_b32 s21, v254, 11
	v_readlane_b32 s22, v254, 12
	v_readlane_b32 s23, v254, 13
	v_readlane_b32 s24, v254, 14
	v_readlane_b32 s25, v254, 15
	v_readlane_b32 s26, v254, 16
	s_add_u32 s0, s16, 0xc0000
	v_mov_b32_e32 v13, v15
	v_lshl_add_u32 v155, v12, 2, 32
	v_lshlrev_b32_e32 v158, 2, v3
	v_cmp_gt_u32_e64 s[6:7], 8, v2
	v_add_u32_e32 v159, 32, v1
	s_addc_u32 s1, s17, 0
	s_movk_i32 s2, 0x6000
	s_mov_b32 s3, 0x30000
	s_mov_b32 s20, 0x2a000
	s_mov_b32 s21, 0x36000
	s_mov_b32 s22, 0x3c000
	s_mov_b32 s23, 0x42000
	s_mov_b32 s24, 0x48000
	s_mov_b32 s25, 0x4e000
	v_mov_b32_e32 v160, 0x6c000
	s_mov_b32 s98, -1
	s_mov_b32 s26, s96
	v_readlane_b32 s13, v254, 3
	v_readlane_b32 s14, v254, 4
	v_readlane_b32 s15, v254, 5
	v_readlane_b32 s18, v254, 8
	v_readlane_b32 s19, v254, 9
	v_readlane_b32 s27, v254, 17
	s_branch .LBB0_17

.LBB0_17:
	s_mul_hi_i32 s12, s26, 0x2aaaaaab
	s_lshr_b32 s13, s12, 31
	s_ashr_i32 s12, s12, 5
	s_add_i32 s12, s12, s13
	s_mul_i32 s13, s12, 0xc0
	s_sub_i32 s13, s26, s13
	s_and_b32 s27, s13, 7
	s_lshl_b32 s28, s27, 8
	s_barrier
	s_cmp_eq_u32 s28, s98
	s_mov_b32 s98, s28
	s_mov_b64 s[14:15], exec
	s_cbranch_scc1 .LBB0_24
	s_and_saveexec_b64 s[14:15], s[4:5]
	s_cbranch_execz .LBB0_24
	v_and_b32_e32 v20, 0xff, v10
	v_lshrrev_b32_e32 v21, 8, v10
	v_lshl_or_b32 v21, v21, 11, v20
	v_or_b32_e32 v21, s28, v21
	v_lshlrev_b32_e32 v21, 2, v21
	global_load_dword v22, v21, s[72:73]
	global_load_dword v23, v21, s[74:75]
	v_add_u32_e32 v41, 0x4000, v21
	global_load_dword v24, v41, s[74:75]
	v_add_u32_e32 v42, 0x8000, v21
	global_load_dword v25, v42, s[74:75]
	v_add_u32_e32 v43, 0xc000, v21
	global_load_dword v26, v43, s[74:75]
	v_add_u32_e32 v44, 0x10000, v21
	global_load_dword v27, v44, s[74:75]
	v_add_u32_e32 v45, 0x14000, v21
	global_load_dword v28, v45, s[74:75]
	v_add_u32_e32 v46, 0x18000, v21
	global_load_dword v29, v46, s[74:75]
	v_add_u32_e32 v47, 0x1c000, v21
	global_load_dword v30, v47, s[74:75]
	s_waitcnt vmcnt(0)
	v_mul_f32_e32 v31, 0xbfb8aa3b, v22
	v_mul_f32_e32 v32, 0xbfb8aa3b, v23
	v_mul_f32_e32 v33, 0xbfb8aa3b, v24
	v_mul_f32_e32 v34, 0xbfb8aa3b, v25
	v_mul_f32_e32 v35, 0xbfb8aa3b, v26
	v_mul_f32_e32 v36, 0xbfb8aa3b, v27
	v_mul_f32_e32 v37, 0xbfb8aa3b, v28
	v_mul_f32_e32 v38, 0xbfb8aa3b, v29
	v_mul_f32_e32 v39, 0xbfb8aa3b, v30
	v_exp_f32_e32 v31, v31
	v_exp_f32_e32 v32, v32
	v_exp_f32_e32 v33, v33
	v_exp_f32_e32 v34, v34
	v_exp_f32_e32 v35, v35
	v_exp_f32_e32 v36, v36
	v_exp_f32_e32 v37, v37
	v_exp_f32_e32 v38, v38
	v_exp_f32_e32 v39, v39
	v_add_f32_e32 v31, 1.0, v31
	v_add_f32_e32 v32, 1.0, v32
	v_add_f32_e32 v33, 1.0, v33
	v_add_f32_e32 v34, 1.0, v34
	v_add_f32_e32 v35, 1.0, v35
	v_add_f32_e32 v36, 1.0, v36
	v_add_f32_e32 v37, 1.0, v37
	v_add_f32_e32 v38, 1.0, v38
	v_add_f32_e32 v39, 1.0, v39
	v_rcp_f32_e32 v31, v31
	v_rcp_f32_e32 v32, v32
	v_rcp_f32_e32 v33, v33
	v_rcp_f32_e32 v34, v34
	v_rcp_f32_e32 v35, v35
	v_rcp_f32_e32 v36, v36
	v_rcp_f32_e32 v37, v37
	v_rcp_f32_e32 v38, v38
	v_rcp_f32_e32 v39, v39
	v_mul_f32_e32 v22, v22, v31
	v_mul_f32_e32 v23, v23, v32
	v_mul_f32_e32 v24, v24, v33
	v_mul_f32_e32 v25, v25, v34
	v_mul_f32_e32 v26, v26, v35
	v_mul_f32_e32 v27, v27, v36
	v_mul_f32_e32 v28, v28, v37
	v_mul_f32_e32 v29, v29, v38
	v_mul_f32_e32 v30, v30, v39
	ds_write_b32 v159, v22
	ds_write_b32 v159, v23 offset:2048
	ds_write_b32 v159, v24 offset:4096
	ds_write_b32 v159, v25 offset:6144
	ds_write_b32 v159, v26 offset:8192
	ds_write_b32 v159, v27 offset:10240
	ds_write_b32 v159, v28 offset:12288
	ds_write_b32 v159, v29 offset:14336
	ds_write_b32 v159, v30 offset:16384
